# rms_rows loads issued together (comparison point)
# speedup vs baseline: 1.0398x; 1.0060x over previous
; __device__ __forceinline__ unsigned pk2(float lo, float hi) { f32x2 v = {lo, hi}; bf16x2_t b = __builtin_convertvector(v, bf16x2_t); return __builtin_bit_cast(unsigned, b); }
; __device__ __forceinline__ float wave_sum_dpp(float v) { v = half32_sum(v); auto r = __builtin_amdgcn_permlane32_swap(asu(v), asu(v), false, false); return asf(r[0]) + asf(r[1]); }
; __device__ __forceinline__ void rms_rows(const Ctx& c, const float* x, const float* gain, bf16_t* out, float* xcopy) {
;     ...
;     for (int m = c.gw; m < M_; m += c.ngw) {
;         const f32x4* xr = (const f32x4*)(x + (size_t)m * D_) + c.lane;
;         f32x4 v[4]; float s = 0.f;
; #pragma unroll
;         for (int j = 0; j < 4; ++j) { v[j] = xr[64 * j]; s += (v[j].x * v[j].x + v[j].y * v[j].y) + (v[j].z * v[j].z + v[j].w * v[j].w); }
;         if (xcopy) { f32x4* xc = (f32x4*)(xcopy + (size_t)m * D_) + c.lane;
; #pragma unroll
;             for (int j = 0; j < 4; ++j) xc[64 * j] = v[j]; }
;         const float r = rsqrtf(wave_sum_dpp(s) * (1.f / D_) + 1e-6f);
;         u32x2* o8 = (u32x2*)(out + (size_t)m * D_) + c.lane;
; #pragma unroll
;         for (int j = 0; j < 4; ++j) { u32x2 w; w.x = pk2(v[j].x * r * gv[j].x, v[j].y * r * gv[j].y); w.y = pk2(v[j].z * r * gv[j].z, v[j].w * r * gv[j].w); o8[64 * j] = w; }
;     }
.LBB0_76:
	global_load_dwordx4 v[22:25], v[20:21], off
	global_load_dwordx4 v[26:29], v[20:21], off offset:1024
	global_load_dwordx4 v[30:33], v[20:21], off offset:2048
	global_load_dwordx4 v[34:37], v[20:21], off offset:3072
	s_add_i32 s10, s10, s30
	s_cmpk_gt_i32 s10, 0x7fff
	v_lshl_add_u64 v[20:21], v[20:21], 0, s[6:7]
	s_waitcnt vmcnt(3)
	v_mul_f32_e32 v1, v23, v23
	v_mul_f32_e32 v40, v25, v25
	v_fmac_f32_e32 v1, v22, v22
	v_fmac_f32_e32 v40, v24, v24
	v_add_f32_e32 v1, v1, v40
	s_waitcnt vmcnt(2)
	v_mul_f32_e32 v40, v27, v27
	v_mul_f32_e32 v41, v29, v29
	v_fmac_f32_e32 v40, v26, v26
	v_fmac_f32_e32 v41, v28, v28
	v_add_f32_e32 v40, v40, v41
	v_add_f32_e32 v1, v1, v40
	s_waitcnt vmcnt(1)
	v_mul_f32_e32 v40, v31, v31
	v_mul_f32_e32 v41, v33, v33
	v_fmac_f32_e32 v40, v30, v30
	v_fmac_f32_e32 v41, v32, v32
	v_add_f32_e32 v40, v40, v41
	v_add_f32_e32 v1, v1, v40
	s_waitcnt vmcnt(0)
	v_mul_f32_e32 v38, v35, v35
	v_mul_f32_e32 v39, v37, v37
	v_fmac_f32_e32 v38, v34, v34
	v_fmac_f32_e32 v39, v36, v36
	v_add_f32_e32 v38, v38, v39
	v_add_f32_e32 v1, v1, v38
	s_nop 1
	v_add_f32_dpp v1, v1, v1 row_ror:8 row_mask:0xf bank_mask:0xf bound_ctrl:1
	s_nop 1
	v_add_f32_dpp v1, v1, v1 row_ror:4 row_mask:0xf bank_mask:0xf bound_ctrl:1
	s_nop 1
	v_add_f32_dpp v1, v1, v1 row_ror:2 row_mask:0xf bank_mask:0xf bound_ctrl:1
	s_nop 1
	v_add_f32_dpp v1, v1, v1 row_ror:1 row_mask:0xf bank_mask:0xf bound_ctrl:1
	v_mov_b32_e32 v38, v1
	s_nop 1
	v_permlane16_swap_b32_e32 v1, v38
	v_add_f32_e32 v1, v1, v38
	v_mov_b32_e32 v38, v1
	s_nop 1
	v_permlane32_swap_b32_e32 v1, v38
	v_add_f32_e32 v1, v1, v38
	v_fmamk_f32 v1, v1, 0x3a800000, v148
	v_cmp_gt_f32_e32 vcc, s33, v1
	v_mul_f32_e32 v38, 0x4b800000, v1
	s_nop 0
	v_cndmask_b32_e32 v1, v1, v38, vcc
	v_rsq_f32_e32 v1, v1
	s_nop 0
	v_mul_f32_e32 v38, 0x45800000, v1
	v_cndmask_b32_e32 v38, v1, v38, vcc
	v_pk_mul_f32 v[22:23], v[22:23], v[38:39] op_sel_hi:[1,0]
	v_pk_mul_f32 v[24:25], v[24:25], v[38:39] op_sel_hi:[1,0]
	v_pk_mul_f32 v[22:23], v[14:15], v[22:23]
	v_pk_mul_f32 v[24:25], v[16:17], v[24:25]
	v_cvt_pk_bf16_f32 v22, v22, v23
	v_cvt_pk_bf16_f32 v23, v24, v25
	global_store_dwordx2 v[18:19], v[22:23], off
	v_pk_mul_f32 v[22:23], v[26:27], v[38:39] op_sel_hi:[1,0]
	v_pk_mul_f32 v[24:25], v[28:29], v[38:39] op_sel_hi:[1,0]
	v_pk_mul_f32 v[22:23], v[10:11], v[22:23]
	v_pk_mul_f32 v[24:25], v[12:13], v[24:25]
	v_cvt_pk_bf16_f32 v22, v22, v23
	v_cvt_pk_bf16_f32 v23, v24, v25
	global_store_dwordx2 v[18:19], v[22:23], off offset:512
	v_pk_mul_f32 v[22:23], v[30:31], v[38:39] op_sel_hi:[1,0]
	v_pk_mul_f32 v[24:25], v[32:33], v[38:39] op_sel_hi:[1,0]
	v_pk_mul_f32 v[22:23], v[6:7], v[22:23]
	v_pk_mul_f32 v[24:25], v[8:9], v[24:25]
	v_cvt_pk_bf16_f32 v22, v22, v23
	v_cvt_pk_bf16_f32 v23, v24, v25
	global_store_dwordx2 v[18:19], v[22:23], off offset:1024
	v_pk_mul_f32 v[22:23], v[34:35], v[38:39] op_sel_hi:[1,0]
	v_pk_mul_f32 v[24:25], v[36:37], v[38:39] op_sel_hi:[1,0]
	v_pk_mul_f32 v[22:23], v[2:3], v[22:23]
	v_pk_mul_f32 v[24:25], v[4:5], v[24:25]
	v_cvt_pk_bf16_f32 v22, v22, v23
	v_cvt_pk_bf16_f32 v23, v24, v25
	global_store_dwordx2 v[18:19], v[22:23], off offset:1536
	v_lshl_add_u64 v[18:19], v[18:19], 0, s[2:3]
	s_cbranch_scc0 .LBB0_76

; #define LAS __attribute__((address_space(3)))
; __device__ __forceinline__ void attn_phase(const Ctx& c, const Params& p, int o, int first, int cidx) {
;     const bf16_t* QH = (const bf16_t*)(c.ws + WS_QR); const bf16_t* KH = (const bf16_t*)(c.ws + WS_KH); const bf16_t* VT = (const bf16_t*)(c.ws + WS_VT); bf16_t* Y = (bf16_t*)(c.ws + WS_AB);
;     const int l31 = c.lane & 31, hh = c.lane >> 5;
;     if (c.bid < first) return;
;     unsigned* cnt = (unsigned*)(c.ws + WS_CTL) + 64 * o + 16 * cidx;
;     LAS bf16_t* sK = (LAS bf16_t*)(c.lds);
;     LAS bf16_t* sVt = (LAS bf16_t*)(c.lds + 26624);
;     LAS unsigned* sU = (LAS unsigned*)(c.lds + 26624 + 18432);
;     const int k0row = c.tid / 12, k0ch = c.tid % 12; const int k1p = c.tid + 512, k1row = k1p / 12, k1ch = k1p % 12; const bool k1on = c.tid < 256;
;     const int vrow = c.tid >> 3, vch = c.tid & 7;
.LBB0_108:
	s_cmp_lt_i32 s94, 0
	s_movk_i32 s0, 0x3ff
	s_mov_b32 s6, 0x2aaaaaab
	s_mov_b32 s36, 0x2100000
	s_cbranch_scc1 .LBB0_136
	v_mul_hi_i32 v2, v166, s6
	v_lshrrev_b32_e32 v3, 31, v2
	v_ashrrev_i32_e32 v2, 1, v2
	v_add_u32_e32 v6, v2, v3
	s_add_u32 s12, s22, 0x1cc00000
	v_mul_lo_u32 v2, v6, 12
	s_addc_u32 s13, s23, 0
	v_sub_u32_e32 v7, v166, v2
	v_add_u32_e32 v2, 0x200, v166
	s_add_u32 s20, s22, 0xe100000
	v_readlane_b32 s2, v255, 39
	v_mul_hi_i32 v3, v2, s6
	s_addc_u32 s21, s23, 0
	v_readlane_b32 s3, v255, 40
	s_lshl_b32 s42, s2, 6
	v_lshrrev_b32_e32 v4, 31, v3
	v_ashrrev_i32_e32 v3, 1, v3
	s_lshl_b64 s[2:3], s[42:43], 2
	v_add_u32_e32 v8, v3, v4
	s_add_u32 s14, s22, s2
	v_mul_lo_u32 v3, v8, 12
	s_movk_i32 s2, 0x100
	s_addc_u32 s15, s23, s3
	v_sub_u32_e32 v9, v2, v3
	v_cmp_gt_i32_e64 s[6:7], s2, v166
	v_ashrrev_i32_e32 v2, 3, v166
	v_mad_i64_i32 v[104:105], s[2:3], v6, s50, 0
	v_mad_i64_i32 v[108:109], s[2:3], v8, s50, 0
	v_ashrrev_i32_e32 v3, 31, v2
	s_movk_i32 s2, 0x68
	v_lshlrev_b64 v[4:5], 14, v[2:3]
	v_mul_lo_u32 v3, v6, s2
	s_movk_i32 s2, 0xd0
	v_lshlrev_b32_e32 v125, 1, v3
	v_lshlrev_b32_e32 v3, 4, v7
	v_mul_lo_u32 v127, v8, s2
	s_movk_i32 s2, 0x90
	v_add3_u32 v126, s80, v125, v3
	v_mul_lo_u32 v3, v2, s2
	v_lshlrev_b32_e32 v2, 4, v164
	v_and_b32_e32 v124, 31, v164
	v_ashrrev_i32_e32 v1, 5, v164
	v_and_b32_e32 v2, 0x70, v2
	v_lshlrev_b32_e32 v110, 3, v9
	v_lshlrev_b32_e32 v128, 4, v9
	v_add3_u32 v129, s80, v3, v2
	v_lshrrev_b32_e32 v251, 4, v166
	v_and_b32_e32 v251, 8, v251
	v_sub_u32_e32 v252, 8, v251
	v_add_u32_e32 v251, v129, v251
	v_add_u32_e32 v252, v129, v252
	v_mul_u32_u24_e32 v3, 0xd0, v124
	v_lshlrev_b32_e32 v9, 4, v1
	v_lshlrev_b32_e32 v102, 3, v1
	v_add3_u32 v130, s80, v3, v9
	v_mul_u32_u24_e32 v3, 0x90, v124
	v_lshl_add_u64 v[4:5], s[22:23], 0, v[4:5]
	v_add3_u32 v131, s80, v3, v102
	v_lshrrev_b32_e32 v250, 1, v124
	v_and_b32_e32 v250, 8, v250
	v_xor_b32_e32 v131, v131, v250
	v_mov_b32_e32 v3, v0
	v_lshl_add_u64 v[2:3], v[4:5], 0, v[2:3]
	s_mov_b64 s[2:3], 0x11100000
	v_lshlrev_b32_e32 v106, 3, v7
	v_add_u32_e32 v7, s80, v127
	v_lshlrev_b32_e32 v112, 2, v1
	v_lshl_add_u64 v[114:115], v[2:3], 0, s[2:3]
	v_readlane_b32 s2, v255, 46
	v_ashrrev_i32_e32 v103, 31, v102
	v_ashrrev_i32_e32 v107, 31, v106
	v_ashrrev_i32_e32 v111, 31, v110
	v_ashrrev_i32_e32 v113, 31, v112
	v_cmp_eq_u32_e64 s[8:9], 0, v166
	s_lshl_b32 s24, s2, 5
	v_add_u32_e32 v132, 64, v8
	v_add_u32_e32 v133, 64, v6
	v_add_u32_e32 v134, v7, v128
	s_branch .LBB0_112

; #define LAS __attribute__((address_space(3)))
; __device__ __forceinline__ void attn_phase(const Ctx& c, const Params& p, int o, int first, int cidx) {
;     ...
;         bf16x8 qf[6]; { const bf16_t* qp = QH + (size_t)(b * T_ + qs + l31) * 768 + h * 96 + 8 * hh;
; #pragma unroll
;             for (int ks = 0; ks < 6; ++ks) qf[ks] = *(const bf16x8*)(qp + 16 * ks); }
;         f32x16 o0 = {}, o1 = {}; float mrun = -INFINITY, lrun = 0.f;
;         const int ntile = 4 * (qblk + 1);
;         const bf16_t* kg = KH + (size_t)(b * T_) * 768 + h * 96; const bf16_t* vg = VT + (size_t)bh * 64 * T_;
;         u32x4 rk0, rk1 = {}, rv;
;         rk0 = *(const u32x4*)(kg + (size_t)k0row * 768 + 8 * k0ch); if (k1on) rk1 = *(const u32x4*)(kg + (size_t)k1row * 768 + 8 * k1ch); rv = *(const u32x4*)(vg + (size_t)vrow * T_ + 8 * vch);
;         *(LAS u32x4*)(sK + k0row * 104 + 8 * k0ch) = rk0; if (k1on) *(LAS u32x4*)(sK + k1row * 104 + 8 * k1ch) = rk1; *(LAS u32x4*)(sVt + vrow * 72 + 8 * vch) = rv;
;         __syncthreads();
.LBB0_117:
	s_or_b64 exec, exec, s[18:19]
	s_lshl_b32 s11, s11, 20
	s_and_b32 s42, s11, 0x1f00000
	v_lshl_add_u64 v[118:119], v[114:115], 0, s[42:43]
	global_load_dwordx4 v[98:101], v[118:119], off
	s_waitcnt vmcnt(0) lgkmcnt(0)
	ds_write_b128 v126, v[90:93]
	s_and_saveexec_b64 s[18:19], s[6:7]
	ds_write_b128 v134, v[94:97]
	s_or_b64 exec, exec, s[18:19]
	v_mov_b32_e32 v14, v0
	v_mov_b32_e32 v15, v0
	v_mov_b32_e32 v1, v0
	v_mov_b32_e32 v2, v0
	v_mov_b32_e32 v3, v0
	v_mov_b32_e32 v4, v0
	v_mov_b32_e32 v5, v0
	v_mov_b32_e32 v6, v0
	v_mov_b32_e32 v7, v0
	v_mov_b32_e32 v8, v0
	v_mov_b32_e32 v9, v0
	v_mov_b32_e32 v10, v0
	v_mov_b32_e32 v11, v0
	v_mov_b32_e32 v12, v0
	v_mov_b32_e32 v13, v0
	v_mov_b64_e32 v[32:33], v[14:15]
	s_lshl_b32 s10, s10, 2
	s_mov_b32 s42, 0
	v_mov_b64_e32 v[30:31], v[12:13]
	v_mov_b64_e32 v[28:29], v[10:11]
	v_mov_b64_e32 v[26:27], v[8:9]
	v_mov_b64_e32 v[24:25], v[6:7]
	v_mov_b64_e32 v[22:23], v[4:5]
	v_mov_b64_e32 v[20:21], v[2:3]
	v_mov_b64_e32 v[18:19], v[0:1]
	v_mov_b64_e32 v[16:17], v[14:15]
	v_ashrrev_i32_e32 v117, 31, v116
	s_sub_i32 s27, 0x80, s10
	v_lshl_add_u64 v[120:121], v[106:107], 1, s[2:3]
	v_lshl_add_u64 v[122:123], v[110:111], 1, s[2:3]
	s_addk_i32 s29, 0x1f1f
	v_or_b32_e32 v135, s26, v124
	v_mov_b32_e32 v136, 0
	v_mov_b32_e32 v137, 0xff800000
	v_mov_b64_e32 v[14:15], v[12:13]
	v_mov_b64_e32 v[12:13], v[10:11]
	v_mov_b64_e32 v[10:11], v[8:9]
	v_mov_b64_e32 v[8:9], v[6:7]
	v_mov_b64_e32 v[6:7], v[4:5]
	v_mov_b64_e32 v[4:5], v[2:3]
	v_mov_b64_e32 v[2:3], v[0:1]
	s_mov_b32 s10, s42
	ds_write_b64 v251, v[98:99] offset:26624
	ds_write_b64 v252, v[100:101] offset:26624
	s_waitcnt lgkmcnt(0)
	s_barrier
	v_readlane_b32 s11, v255, 5
	s_cmp_ge_u32 s11, 4
	s_cbranch_scc1 .Lsb_loop

; #define LAS __attribute__((address_space(3)))
; __device__ __forceinline__ int crow(int r, int hi) { return (r & 3) + 8 * (r >> 2) + 4 * hi; }
; #define PV_STEP(OACC, mm, ktt, ss, PF) do { OACC = __builtin_amdgcn_mfma_f32_32x32x16_bf16(ldA_perm(vb + (mm) * 32 * 72 + 32 * (ktt) + 16 * (ss)), PF, OACC, 0, 0, 0); } while (0)
; __device__ __forceinline__ void attn_phase(const Ctx& c, const Params& p, int o, int first, int cidx) {
;     ...
;             if (kv0 <= qs + 31) {
;                 const LAS bf16_t* kb = sK + buf * 6656 + l31 * 104 + 8 * hh; const LAS bf16_t* vb = sVt + buf * 4608 + l31 * 72 + 4 * hh;
;                 f32x16 p0 = {}, p1 = {};
; #pragma unroll
;                 for (int ks = 0; ks < 6; ++ks) { const bf16x8 k0 = *(const LAS bf16x8*)(kb + 16 * ks); const bf16x8 k1 = *(const LAS bf16x8*)(kb + 32 * 104 + 16 * ks);
;                     p0 = __builtin_amdgcn_mfma_f32_32x32x16_bf16(k0, qf[ks], p0, 0, 0, 0); p1 = __builtin_amdgcn_mfma_f32_32x32x16_bf16(k1, qf[ks], p1, 0, 0, 0); }
;                 if (kv0 + 63 > qs) { const int q = qs + l31;
; #pragma unroll
;                     for (int r = 0; r < 16; ++r) { const int kv = kv0 + crow(r, hh); if (kv > q) p0[r] = -INFINITY; if (kv + 32 > q) p1[r] = -INFINITY; } }
;     ...
;                 PV_STEP(o0, 0, 0, 0, pf00); PV_STEP(o0, 0, 0, 1, pf01); PV_STEP(o0, 0, 1, 0, pf10); PV_STEP(o0, 0, 1, 1, pf11);
;                 PV_STEP(o1, 1, 0, 0, pf00); PV_STEP(o1, 1, 0, 1, pf01); PV_STEP(o1, 1, 1, 0, pf10); PV_STEP(o1, 1, 1, 1, pf11);
.LBB0_124:
	s_and_b32 s18, s10, 1
	s_cmp_gt_i32 s42, s29
	s_cbranch_scc1 .LBB0_130
	s_mul_i32 s10, s18, 0x3400
	s_mul_i32 s11, s18, 0x2400
	v_add_u32_e32 v1, s10, v130
	v_add_u32_e32 v142, s11, v131
	ds_read_b128 v[200:203], v1
	ds_read_b128 v[204:207], v1 offset:6656
	ds_read_b128 v[208:211], v1 offset:32
	ds_read_b128 v[212:215], v1 offset:6688
	ds_read_b128 v[216:219], v1 offset:64
	ds_read_b128 v[220:223], v1 offset:6720
	ds_read_b128 v[224:227], v1 offset:96
	ds_read_b128 v[228:231], v1 offset:6752
	ds_read_b128 v[232:235], v1 offset:128
	ds_read_b128 v[236:239], v1 offset:6784
	ds_read_b128 v[240:243], v1 offset:160
	ds_read_b128 v[244:247], v1 offset:6816
	v_add_u32_e32 v143, 0x7a00, v142
	v_add_u32_e32 v142, 0x6800, v142
	s_add_i32 s10, s42, 63
	s_cmp_le_i32 s10, s26
	s_waitcnt lgkmcnt(10)
	v_mfma_f32_32x32x16_bf16 v[50:65], v[200:203], v[66:69], 0
	v_mfma_f32_32x32x16_bf16 v[34:49], v[204:207], v[66:69], 0
	s_waitcnt lgkmcnt(8)
	v_mfma_f32_32x32x16_bf16 v[50:65], v[208:211], v[70:73], v[50:65]
	v_mfma_f32_32x32x16_bf16 v[34:49], v[212:215], v[70:73], v[34:49]
	s_waitcnt lgkmcnt(6)
	v_mfma_f32_32x32x16_bf16 v[50:65], v[216:219], v[74:77], v[50:65]
	v_mfma_f32_32x32x16_bf16 v[34:49], v[220:223], v[74:77], v[34:49]
	ds_read_b64 v[200:201], v142
	ds_read_b64 v[202:203], v142 offset:16
	ds_read_b64 v[204:205], v142 offset:32
	ds_read_b64 v[206:207], v142 offset:48
	s_waitcnt lgkmcnt(8)
	v_mfma_f32_32x32x16_bf16 v[50:65], v[224:227], v[78:81], v[50:65]
	v_mfma_f32_32x32x16_bf16 v[34:49], v[228:231], v[78:81], v[34:49]
	ds_read_b64 v[208:209], v142 offset:64
	ds_read_b64 v[210:211], v142 offset:80
	ds_read_b64 v[212:213], v142 offset:96
	ds_read_b64 v[214:215], v142 offset:112
	s_waitcnt lgkmcnt(10)
	v_mfma_f32_32x32x16_bf16 v[50:65], v[232:235], v[82:85], v[50:65]
	v_mfma_f32_32x32x16_bf16 v[34:49], v[236:239], v[82:85], v[34:49]
	ds_read_b64 v[216:217], v143
	ds_read_b64 v[218:219], v143 offset:16
	ds_read_b64 v[220:221], v143 offset:32
	ds_read_b64 v[222:223], v143 offset:48
	s_waitcnt lgkmcnt(12)
	v_mfma_f32_32x32x16_bf16 v[50:65], v[240:243], v[86:89], v[50:65]
	v_mfma_f32_32x32x16_bf16 v[34:49], v[244:247], v[86:89], v[34:49]
	ds_read_b64 v[224:225], v143 offset:64
	ds_read_b64 v[226:227], v143 offset:80
	ds_read_b64 v[228:229], v143 offset:96
	s_waitcnt lgkmcnt(7)
	ds_read_b64 v[230:231], v143 offset:112
	s_cbranch_scc1 .LBB0_127
	v_add_u32_e32 v1, s42, v112
	v_add_u32_e32 v138, 32, v1
	v_cmp_le_i32_e32 vcc, v138, v135
	v_add_u32_e32 v138, 33, v1
	s_nop 6
	v_cndmask_b32_e32 v34, v173, v34, vcc
	v_cmp_lt_i32_e32 vcc, v1, v135
	s_nop 1
	v_cndmask_b32_e32 v51, v173, v51, vcc
	v_cmp_le_i32_e32 vcc, v1, v135
	s_nop 1
	v_cndmask_b32_e32 v50, v173, v50, vcc
	v_cmp_le_i32_e32 vcc, v138, v135
	v_add_u32_e32 v138, 2, v1
	s_nop 0
	v_cndmask_b32_e32 v35, v173, v35, vcc
	v_cmp_le_i32_e32 vcc, v138, v135
	v_add_u32_e32 v138, 34, v1
	s_nop 0
	v_cndmask_b32_e32 v52, v173, v52, vcc
	v_cmp_le_i32_e32 vcc, v138, v135
	v_add_u32_e32 v138, 3, v1
	s_nop 0
	v_cndmask_b32_e32 v36, v173, v36, vcc
	v_cmp_le_i32_e32 vcc, v138, v135
	v_add_u32_e32 v138, 35, v1
	s_nop 0
	v_cndmask_b32_e32 v53, v173, v53, vcc
	v_cmp_le_i32_e32 vcc, v138, v135
	v_add_u32_e32 v138, 8, v1
	s_nop 0
	v_cndmask_b32_e32 v37, v173, v37, vcc
	v_cmp_le_i32_e32 vcc, v138, v135
	v_add_u32_e32 v138, 40, v1
	s_nop 0
	v_cndmask_b32_e32 v54, v173, v54, vcc
	v_cmp_le_i32_e32 vcc, v138, v135
	v_add_u32_e32 v138, 9, v1
	s_nop 0
	v_cndmask_b32_e32 v38, v173, v38, vcc
	v_cmp_le_i32_e32 vcc, v138, v135
	v_add_u32_e32 v138, 41, v1
	s_nop 0
	v_cndmask_b32_e32 v55, v173, v55, vcc
	v_cmp_le_i32_e32 vcc, v138, v135
	v_add_u32_e32 v138, 10, v1
	s_nop 0
	v_cndmask_b32_e32 v39, v173, v39, vcc
	v_cmp_le_i32_e32 vcc, v138, v135
	v_add_u32_e32 v138, 42, v1
	s_nop 0
	v_cndmask_b32_e32 v56, v173, v56, vcc
	v_cmp_le_i32_e32 vcc, v138, v135
	v_add_u32_e32 v138, 11, v1
	s_nop 0
	v_cndmask_b32_e32 v40, v173, v40, vcc
	v_cmp_le_i32_e32 vcc, v138, v135
	v_add_u32_e32 v138, 43, v1
	s_nop 0
	v_cndmask_b32_e32 v57, v173, v57, vcc
	v_cmp_le_i32_e32 vcc, v138, v135
	v_add_u32_e32 v138, 16, v1
	s_nop 0
	v_cndmask_b32_e32 v41, v173, v41, vcc
	v_cmp_le_i32_e32 vcc, v138, v135
	v_add_u32_e32 v138, 48, v1
	s_nop 0
	v_cndmask_b32_e32 v58, v173, v58, vcc
	v_cmp_le_i32_e32 vcc, v138, v135
	v_add_u32_e32 v138, 17, v1
	s_nop 0
	v_cndmask_b32_e32 v42, v173, v42, vcc
	v_cmp_le_i32_e32 vcc, v138, v135
	v_add_u32_e32 v138, 49, v1
	s_nop 0
	v_cndmask_b32_e32 v59, v173, v59, vcc
	v_cmp_le_i32_e32 vcc, v138, v135
	v_add_u32_e32 v138, 18, v1
	s_nop 0
	v_cndmask_b32_e32 v43, v173, v43, vcc
	v_cmp_le_i32_e32 vcc, v138, v135
	v_add_u32_e32 v138, 50, v1
	s_nop 0
	v_cndmask_b32_e32 v60, v173, v60, vcc
	v_cmp_le_i32_e32 vcc, v138, v135
	v_add_u32_e32 v138, 19, v1
	s_nop 0
	v_cndmask_b32_e32 v44, v173, v44, vcc
	v_cmp_le_i32_e32 vcc, v138, v135
	v_add_u32_e32 v138, 51, v1
	s_nop 0
	v_cndmask_b32_e32 v61, v173, v61, vcc
	v_cmp_le_i32_e32 vcc, v138, v135
	v_add_u32_e32 v138, 24, v1
	s_nop 0
	v_cndmask_b32_e32 v45, v173, v45, vcc
	v_cmp_le_i32_e32 vcc, v138, v135
	v_add_u32_e32 v138, 56, v1
	s_nop 0
	v_cndmask_b32_e32 v62, v173, v62, vcc
	v_cmp_le_i32_e32 vcc, v138, v135
	v_add_u32_e32 v138, 25, v1
	s_nop 0
	v_cndmask_b32_e32 v46, v173, v46, vcc
	v_cmp_le_i32_e32 vcc, v138, v135
	v_add_u32_e32 v138, 57, v1
	s_nop 0
	v_cndmask_b32_e32 v63, v173, v63, vcc
	v_cmp_le_i32_e32 vcc, v138, v135
	v_add_u32_e32 v138, 26, v1
	s_nop 0
	v_cndmask_b32_e32 v47, v173, v47, vcc
	v_cmp_le_i32_e32 vcc, v138, v135
	v_add_u32_e32 v138, 58, v1
	s_nop 0
	v_cndmask_b32_e32 v64, v173, v64, vcc
	v_cmp_le_i32_e32 vcc, v138, v135
	v_add_u32_e32 v138, 27, v1
	v_add_u32_e32 v1, 59, v1
	v_cndmask_b32_e32 v48, v173, v48, vcc
	v_cmp_le_i32_e32 vcc, v138, v135
	s_nop 1
	v_cndmask_b32_e32 v65, v173, v65, vcc
	v_cmp_le_i32_e32 vcc, v1, v135
	s_nop 1
	v_cndmask_b32_e32 v49, v173, v49, vcc

; #define LAS __attribute__((address_space(3)))
; __device__ __forceinline__ void attn_phase(const Ctx& c, const Params& p, int o, int first, int cidx) {
;     ...
;             if (kt + 1 < ntile) { const int nb = buf ^ 1;
;                 *(LAS u32x4*)(sK + nb * 6656 + k0row * 104 + 8 * k0ch) = rk0; if (k1on) *(LAS u32x4*)(sK + nb * 6656 + k1row * 104 + 8 * k1ch) = rk1; *(LAS u32x4*)(sVt + nb * 4608 + vrow * 72 + 8 * vch) = rv; }
.LBB0_131:
	s_xor_b32 s10, s18, 1
	s_mul_i32 s2, s10, 0x3400
	s_add_i32 s11, s80, s2
	v_lshlrev_b32_e32 v34, 1, v106
	v_add3_u32 v34, s11, v125, v34
	s_waitcnt vmcnt(0) lgkmcnt(0)
	ds_write_b128 v34, v[90:93]
	s_and_saveexec_b64 s[2:3], s[6:7]
	v_add3_u32 v34, s11, v127, v128
	ds_write_b128 v34, v[94:97]
	s_or_b64 exec, exec, s[2:3]
	s_mulk_i32 s10, 0x2400
	v_add_u32_e32 v34, s10, v251
	ds_write_b64 v34, v[98:99] offset:26624
	v_add_u32_e32 v34, s10, v252
	ds_write_b64 v34, v[100:101] offset:26624

; #define LAS __attribute__((address_space(3)))
; __device__ __forceinline__ int crow(int r, int hi) { return (r & 3) + 8 * (r >> 2) + 4 * hi; }
; #define PV_STEP(OACC, mm, ktt, ss, PF) do { OACC = __builtin_amdgcn_mfma_f32_32x32x16_bf16(ldA_perm(vb + (mm) * 32 * 72 + 32 * (ktt) + 16 * (ss)), PF, OACC, 0, 0, 0); } while (0)
; __device__ __forceinline__ void attn_phase(const Ctx& c, const Params& p, int o, int first, int cidx) {
;     ...
;             if (kv0 <= qs + 31) {
;                 const LAS bf16_t* kb = sK + buf * 6656 + l31 * 104 + 8 * hh; const LAS bf16_t* vb = sVt + buf * 4608 + l31 * 72 + 4 * hh;
;                 f32x16 p0 = {}, p1 = {};
; #pragma unroll
;                 for (int ks = 0; ks < 6; ++ks) { const bf16x8 k0 = *(const LAS bf16x8*)(kb + 16 * ks); const bf16x8 k1 = *(const LAS bf16x8*)(kb + 32 * 104 + 16 * ks);
;                     p0 = __builtin_amdgcn_mfma_f32_32x32x16_bf16(k0, qf[ks], p0, 0, 0, 0); p1 = __builtin_amdgcn_mfma_f32_32x32x16_bf16(k1, qf[ks], p1, 0, 0, 0); }
;                 if (kv0 + 63 > qs) { const int q = qs + l31;
; #pragma unroll
;                     for (int r = 0; r < 16; ++r) { const int kv = kv0 + crow(r, hh); if (kv > q) p0[r] = -INFINITY; if (kv + 32 > q) p1[r] = -INFINITY; } }
;     ...
;                 PV_STEP(o0, 0, 0, 0, pf00); PV_STEP(o0, 0, 0, 1, pf01); PV_STEP(o0, 0, 1, 0, pf10); PV_STEP(o0, 0, 1, 1, pf11);
;                 PV_STEP(o1, 1, 0, 0, pf00); PV_STEP(o1, 1, 0, 1, pf01); PV_STEP(o1, 1, 1, 0, pf10); PV_STEP(o1, 1, 1, 1, pf11);
.Lsb_nosm:
	s_cmp_gt_i32 s42, s29
	s_cbranch_scc1 .Lsb_noqk
	s_mul_i32 s10, s18, 0x3400
	s_mul_i32 s11, s18, 0x2400
	v_add_u32_e32 v1, s10, v130
	v_add_u32_e32 v142, s11, v131
	ds_read_b128 v[200:203], v1
	ds_read_b128 v[204:207], v1 offset:6656
	ds_read_b128 v[208:211], v1 offset:32
	ds_read_b128 v[212:215], v1 offset:6688
	ds_read_b128 v[216:219], v1 offset:64
	ds_read_b128 v[220:223], v1 offset:6720
	ds_read_b128 v[224:227], v1 offset:96
	ds_read_b128 v[228:231], v1 offset:6752
	ds_read_b128 v[232:235], v1 offset:128
	ds_read_b128 v[236:239], v1 offset:6784
	ds_read_b128 v[240:243], v1 offset:160
	ds_read_b128 v[244:247], v1 offset:6816
	v_add_u32_e32 v143, 0x7a00, v142
	v_add_u32_e32 v142, 0x6800, v142
	s_add_i32 s10, s42, 63
	s_cmp_le_i32 s10, s26
	s_waitcnt lgkmcnt(10)
	v_mfma_f32_32x32x16_bf16 v[50:65], v[200:203], v[66:69], 0
	v_mfma_f32_32x32x16_bf16 v[34:49], v[204:207], v[66:69], 0
	s_waitcnt lgkmcnt(8)
	v_mfma_f32_32x32x16_bf16 v[50:65], v[208:211], v[70:73], v[50:65]
	v_mfma_f32_32x32x16_bf16 v[34:49], v[212:215], v[70:73], v[34:49]
	s_waitcnt lgkmcnt(6)
	v_mfma_f32_32x32x16_bf16 v[50:65], v[216:219], v[74:77], v[50:65]
	v_mfma_f32_32x32x16_bf16 v[34:49], v[220:223], v[74:77], v[34:49]
	ds_read_b64 v[200:201], v142
	ds_read_b64 v[202:203], v142 offset:16
	ds_read_b64 v[204:205], v142 offset:32
	ds_read_b64 v[206:207], v142 offset:48
	s_waitcnt lgkmcnt(8)
	v_mfma_f32_32x32x16_bf16 v[50:65], v[224:227], v[78:81], v[50:65]
	v_mfma_f32_32x32x16_bf16 v[34:49], v[228:231], v[78:81], v[34:49]
	ds_read_b64 v[208:209], v142 offset:64
	ds_read_b64 v[210:211], v142 offset:80
	ds_read_b64 v[212:213], v142 offset:96
	ds_read_b64 v[214:215], v142 offset:112
	s_waitcnt lgkmcnt(10)
	v_mfma_f32_32x32x16_bf16 v[50:65], v[232:235], v[82:85], v[50:65]
	v_mfma_f32_32x32x16_bf16 v[34:49], v[236:239], v[82:85], v[34:49]
	ds_read_b64 v[216:217], v143
	ds_read_b64 v[218:219], v143 offset:16
	ds_read_b64 v[220:221], v143 offset:32
	ds_read_b64 v[222:223], v143 offset:48
	s_waitcnt lgkmcnt(12)
	v_mfma_f32_32x32x16_bf16 v[50:65], v[240:243], v[86:89], v[50:65]
	v_mfma_f32_32x32x16_bf16 v[34:49], v[244:247], v[86:89], v[34:49]
	ds_read_b64 v[224:225], v143 offset:64
	ds_read_b64 v[226:227], v143 offset:80
	ds_read_b64 v[228:229], v143 offset:96
	s_waitcnt lgkmcnt(7)
	ds_read_b64 v[230:231], v143 offset:112
	s_cbranch_scc1 .Lsb_nomask
	v_add_u32_e32 v1, s42, v112
	v_add_u32_e32 v138, 32, v1
	v_cmp_le_i32_e32 vcc, v138, v135
	v_add_u32_e32 v138, 33, v1
	s_nop 6
	v_cndmask_b32_e32 v34, v173, v34, vcc
	v_cmp_lt_i32_e32 vcc, v1, v135
	s_nop 1
	v_cndmask_b32_e32 v51, v173, v51, vcc
	v_cmp_le_i32_e32 vcc, v1, v135
	s_nop 1
	v_cndmask_b32_e32 v50, v173, v50, vcc
	v_cmp_le_i32_e32 vcc, v138, v135
	v_add_u32_e32 v138, 2, v1
	s_nop 0
	v_cndmask_b32_e32 v35, v173, v35, vcc
	v_cmp_le_i32_e32 vcc, v138, v135
	v_add_u32_e32 v138, 34, v1
	s_nop 0
	v_cndmask_b32_e32 v52, v173, v52, vcc
	v_cmp_le_i32_e32 vcc, v138, v135
	v_add_u32_e32 v138, 3, v1
	s_nop 0
	v_cndmask_b32_e32 v36, v173, v36, vcc
	v_cmp_le_i32_e32 vcc, v138, v135
	v_add_u32_e32 v138, 35, v1
	s_nop 0
	v_cndmask_b32_e32 v53, v173, v53, vcc
	v_cmp_le_i32_e32 vcc, v138, v135
	v_add_u32_e32 v138, 8, v1
	s_nop 0
	v_cndmask_b32_e32 v37, v173, v37, vcc
	v_cmp_le_i32_e32 vcc, v138, v135
	v_add_u32_e32 v138, 40, v1
	s_nop 0
	v_cndmask_b32_e32 v54, v173, v54, vcc
	v_cmp_le_i32_e32 vcc, v138, v135
	v_add_u32_e32 v138, 9, v1
	s_nop 0
	v_cndmask_b32_e32 v38, v173, v38, vcc
	v_cmp_le_i32_e32 vcc, v138, v135
	v_add_u32_e32 v138, 41, v1
	s_nop 0
	v_cndmask_b32_e32 v55, v173, v55, vcc
	v_cmp_le_i32_e32 vcc, v138, v135
	v_add_u32_e32 v138, 10, v1
	s_nop 0
	v_cndmask_b32_e32 v39, v173, v39, vcc
	v_cmp_le_i32_e32 vcc, v138, v135
	v_add_u32_e32 v138, 42, v1
	s_nop 0
	v_cndmask_b32_e32 v56, v173, v56, vcc
	v_cmp_le_i32_e32 vcc, v138, v135
	v_add_u32_e32 v138, 11, v1
	s_nop 0
	v_cndmask_b32_e32 v40, v173, v40, vcc
	v_cmp_le_i32_e32 vcc, v138, v135
	v_add_u32_e32 v138, 43, v1
	s_nop 0
	v_cndmask_b32_e32 v57, v173, v57, vcc
	v_cmp_le_i32_e32 vcc, v138, v135
	v_add_u32_e32 v138, 16, v1
	s_nop 0
	v_cndmask_b32_e32 v41, v173, v41, vcc
	v_cmp_le_i32_e32 vcc, v138, v135
	v_add_u32_e32 v138, 48, v1
	s_nop 0
	v_cndmask_b32_e32 v58, v173, v58, vcc
	v_cmp_le_i32_e32 vcc, v138, v135
	v_add_u32_e32 v138, 17, v1
	s_nop 0
	v_cndmask_b32_e32 v42, v173, v42, vcc
	v_cmp_le_i32_e32 vcc, v138, v135
	v_add_u32_e32 v138, 49, v1
	s_nop 0
	v_cndmask_b32_e32 v59, v173, v59, vcc
	v_cmp_le_i32_e32 vcc, v138, v135
	v_add_u32_e32 v138, 18, v1
	s_nop 0
	v_cndmask_b32_e32 v43, v173, v43, vcc
	v_cmp_le_i32_e32 vcc, v138, v135
	v_add_u32_e32 v138, 50, v1
	s_nop 0
	v_cndmask_b32_e32 v60, v173, v60, vcc
	v_cmp_le_i32_e32 vcc, v138, v135
	v_add_u32_e32 v138, 19, v1
	s_nop 0
	v_cndmask_b32_e32 v44, v173, v44, vcc
	v_cmp_le_i32_e32 vcc, v138, v135
	v_add_u32_e32 v138, 51, v1
	s_nop 0
	v_cndmask_b32_e32 v61, v173, v61, vcc
	v_cmp_le_i32_e32 vcc, v138, v135
	v_add_u32_e32 v138, 24, v1
	s_nop 0
	v_cndmask_b32_e32 v45, v173, v45, vcc
	v_cmp_le_i32_e32 vcc, v138, v135
	v_add_u32_e32 v138, 56, v1
	s_nop 0
	v_cndmask_b32_e32 v62, v173, v62, vcc
	v_cmp_le_i32_e32 vcc, v138, v135
	v_add_u32_e32 v138, 25, v1
	s_nop 0
	v_cndmask_b32_e32 v46, v173, v46, vcc
	v_cmp_le_i32_e32 vcc, v138, v135
	v_add_u32_e32 v138, 57, v1
	s_nop 0
	v_cndmask_b32_e32 v63, v173, v63, vcc
	v_cmp_le_i32_e32 vcc, v138, v135
	v_add_u32_e32 v138, 26, v1
	s_nop 0
	v_cndmask_b32_e32 v47, v173, v47, vcc
	v_cmp_le_i32_e32 vcc, v138, v135
	v_add_u32_e32 v138, 58, v1
	s_nop 0
	v_cndmask_b32_e32 v64, v173, v64, vcc
	v_cmp_le_i32_e32 vcc, v138, v135
	v_add_u32_e32 v138, 27, v1
	v_add_u32_e32 v1, 59, v1
	v_cndmask_b32_e32 v48, v173, v48, vcc
	v_cmp_le_i32_e32 vcc, v138, v135
	s_nop 1
	v_cndmask_b32_e32 v65, v173, v65, vcc
	v_cmp_le_i32_e32 vcc, v1, v135
	s_nop 1
	v_cndmask_b32_e32 v49, v173, v49, vcc

; #define LAS __attribute__((address_space(3)))
; __device__ __forceinline__ void attn_phase(const Ctx& c, const Params& p, int o, int first, int cidx) {
;     ...
;             if (kt + 1 < ntile) { const int nb = buf ^ 1;
;                 *(LAS u32x4*)(sK + nb * 6656 + k0row * 104 + 8 * k0ch) = rk0; if (k1on) *(LAS u32x4*)(sK + nb * 6656 + k1row * 104 + 8 * k1ch) = rk1; *(LAS u32x4*)(sVt + nb * 4608 + vrow * 72 + 8 * vch) = rv; }
.Lsb_st:
	s_xor_b32 s10, s18, 1
	s_mul_i32 s2, s10, 0x3400
	s_add_i32 s11, s80, s2
	v_lshlrev_b32_e32 v248, 1, v106
	v_add3_u32 v248, s11, v125, v248
	s_waitcnt vmcnt(0) lgkmcnt(0)
	ds_write_b128 v248, v[90:93]
	s_and_saveexec_b64 s[2:3], s[6:7]
	v_add3_u32 v248, s11, v127, v128
	ds_write_b128 v248, v[94:97]
	s_or_b64 exec, exec, s[2:3]
	s_mulk_i32 s10, 0x2400
	v_add_u32_e32 v248, s10, v251
	ds_write_b64 v248, v[98:99] offset:26624
	v_add_u32_e32 v248, s10, v252
	ds_write_b64 v248, v[100:101] offset:26624
